# ssm phases: interleaved accumulate chains in the chunk-state scan, merged complex-multiply FMA and deeper LDS prefetch in the output scan, batched fragment reads
# speedup vs baseline: 1.0139x; 1.0139x over previous
; #define LAS __attribute__((address_space(3)))
; __device__ __forceinline__ unsigned cvt_pk_bf16(float lo, float hi) { f32x2 v = {lo, hi}; bf16x2_t b = __builtin_convertvector(v, bf16x2_t); return __builtin_bit_cast(unsigned, b); }
; template <bool PASSC>
; __device__ __forceinline__ void ssm_task_old(int task, const SsmW& W, const bf16_t* U, f32x2* SST, bf16_t* YS, LAS unsigned char* wl, int lane) {
;     ...
; #pragma unroll 1
;     for (int half = 0; half < 2; ++half) {
; #pragma unroll 4
;         for (int s = 0; s < 32; ++s) {
;             const LAS f32x4* ur = (const LAS f32x4*)(uL + (half * 32 + s) * 16);
;             float br_ = 0.f, bi_ = 0.f;
; #pragma unroll
;             for (int q = 0; q < 4; ++q) { const f32x4 uv = ur[q];
; #pragma unroll
;                 for (int j = 0; j < 4; ++j) { br_ = fmaf(bbr[4 * q + j], uv[j], br_); bi_ = fmaf(bbi[4 * q + j], uv[j], bi_); } }
;             const float nr = ar * xr - ai * xi + br_, ni = ar * xi + ai * xr + bi_; xr = nr; xi = ni;
;             if (PASSC) *(LAS unsigned*)(xb + s * 272 + 4 * lane) = cvt_pk_bf16(xr, xi);
;         }
;     ...
;     if (!PASSC) SST[((size_t)(b * 16 + g) * 128 + c) * 64 + lane] = (f32x2){xr, xi};
.LBB0_436:
	s_add_i32 s25, s21, s24
	v_mov_b32_e32 v60, s25
	ds_read_b128 v[42:45], v60
	ds_read_b128 v[46:49], v60 offset:16
	ds_read_b128 v[50:53], v60 offset:32
	ds_read_b128 v[54:57], v60 offset:48
	ds_read_b128 v[62:65], v60 offset:64
	ds_read_b128 v[66:69], v60 offset:80
	ds_read_b128 v[70:73], v60 offset:96
	ds_read_b128 v[74:77], v60 offset:112
	s_waitcnt lgkmcnt(7)
	v_pk_fma_f32 v[58:59], v[36:37], v[42:43], 0 op_sel_hi:[1,0,0]
	s_waitcnt lgkmcnt(3)
	v_pk_fma_f32 v[78:79], v[36:37], v[62:63], 0 op_sel_hi:[1,0,0]
	ds_read_b128 v[118:121], v60 offset:128
	ds_read_b128 v[122:125], v60 offset:144
	ds_read_b128 v[126:129], v60 offset:160
	ds_read_b128 v[130:133], v60 offset:176
	ds_read_b128 v[134:137], v60 offset:192
	ds_read_b128 v[138:141], v60 offset:208
	ds_read_b128 v[142:145], v60 offset:224
	ds_read_b128 v[146:149], v60 offset:240
	v_pk_mul_f32 v[80:81], v[6:7], v[38:39] op_sel:[0,1]
	v_pk_fma_f32 v[58:59], v[28:29], v[42:43], v[58:59] op_sel:[0,1,0]
	v_pk_fma_f32 v[78:79], v[28:29], v[62:63], v[78:79] op_sel:[0,1,0]
	v_pk_fma_f32 v[82:83], v[34:35], v[38:39], v[80:81] op_sel_hi:[1,0,1] neg_lo:[0,0,1]
	v_pk_fma_f32 v[58:59], v[24:25], v[44:45], v[58:59] op_sel_hi:[1,0,1]
	v_pk_fma_f32 v[78:79], v[24:25], v[64:65], v[78:79] op_sel_hi:[1,0,1]
	v_pk_fma_f32 v[58:59], v[26:27], v[44:45], v[58:59] op_sel:[0,1,0]
	v_pk_fma_f32 v[78:79], v[26:27], v[64:65], v[78:79] op_sel:[0,1,0]
	s_waitcnt lgkmcnt(10)
	v_pk_fma_f32 v[58:59], v[30:31], v[46:47], v[58:59] op_sel_hi:[1,0,1]
	v_pk_fma_f32 v[78:79], v[30:31], v[66:67], v[78:79] op_sel_hi:[1,0,1]
	v_pk_fma_f32 v[58:59], v[20:21], v[46:47], v[58:59] op_sel:[0,1,0]
	v_pk_fma_f32 v[78:79], v[20:21], v[66:67], v[78:79] op_sel:[0,1,0]
	v_pk_fma_f32 v[58:59], v[16:17], v[48:49], v[58:59] op_sel_hi:[1,0,1]
	v_pk_fma_f32 v[78:79], v[16:17], v[68:69], v[78:79] op_sel_hi:[1,0,1]
	v_pk_fma_f32 v[58:59], v[18:19], v[48:49], v[58:59] op_sel:[0,1,0]
	v_pk_fma_f32 v[78:79], v[18:19], v[68:69], v[78:79] op_sel:[0,1,0]
	s_waitcnt lgkmcnt(9)
	v_pk_fma_f32 v[58:59], v[22:23], v[50:51], v[58:59] op_sel_hi:[1,0,1]
	v_pk_fma_f32 v[78:79], v[22:23], v[70:71], v[78:79] op_sel_hi:[1,0,1]
	v_pk_fma_f32 v[58:59], v[12:13], v[50:51], v[58:59] op_sel:[0,1,0]
	v_pk_fma_f32 v[78:79], v[12:13], v[70:71], v[78:79] op_sel:[0,1,0]
	v_pk_fma_f32 v[58:59], v[8:9], v[52:53], v[58:59] op_sel_hi:[1,0,1]
	v_pk_fma_f32 v[78:79], v[8:9], v[72:73], v[78:79] op_sel_hi:[1,0,1]
	v_pk_fma_f32 v[58:59], v[10:11], v[52:53], v[58:59] op_sel:[0,1,0]
	v_pk_fma_f32 v[78:79], v[10:11], v[72:73], v[78:79] op_sel:[0,1,0]
	s_waitcnt lgkmcnt(8)
	v_pk_fma_f32 v[58:59], v[14:15], v[54:55], v[58:59] op_sel_hi:[1,0,1]
	v_pk_fma_f32 v[78:79], v[14:15], v[74:75], v[78:79] op_sel_hi:[1,0,1]
	v_pk_fma_f32 v[58:59], v[4:5], v[54:55], v[58:59] op_sel:[0,1,0]
	v_pk_fma_f32 v[78:79], v[4:5], v[74:75], v[78:79] op_sel:[0,1,0]
	v_pk_fma_f32 v[58:59], v[0:1], v[56:57], v[58:59] op_sel_hi:[1,0,1]
	v_pk_fma_f32 v[78:79], v[0:1], v[76:77], v[78:79] op_sel_hi:[1,0,1]
	v_pk_fma_f32 v[58:59], v[2:3], v[56:57], v[58:59] op_sel:[0,1,0]
	v_pk_fma_f32 v[78:79], v[2:3], v[76:77], v[78:79] op_sel:[0,1,0]
	v_pk_add_f32 v[38:39], v[82:83], v[58:59]
	s_nop 0
	v_pk_mul_f32 v[80:81], v[6:7], v[38:39] op_sel:[0,1]
	s_nop 0
	v_pk_fma_f32 v[82:83], v[34:35], v[38:39], v[80:81] op_sel_hi:[1,0,1] neg_lo:[0,0,1]
	s_nop 0
	v_pk_add_f32 v[38:39], v[82:83], v[78:79]
	s_addk_i32 s24, 0x100
	s_waitcnt lgkmcnt(7)
	v_pk_fma_f32 v[58:59], v[36:37], v[118:119], 0 op_sel_hi:[1,0,0]
	s_waitcnt lgkmcnt(3)
	v_pk_fma_f32 v[78:79], v[36:37], v[134:135], 0 op_sel_hi:[1,0,0]
	v_pk_mul_f32 v[80:81], v[6:7], v[38:39] op_sel:[0,1]
	v_pk_fma_f32 v[58:59], v[28:29], v[118:119], v[58:59] op_sel:[0,1,0]
	v_pk_fma_f32 v[78:79], v[28:29], v[134:135], v[78:79] op_sel:[0,1,0]
	v_pk_fma_f32 v[82:83], v[34:35], v[38:39], v[80:81] op_sel_hi:[1,0,1] neg_lo:[0,0,1]
	v_pk_fma_f32 v[58:59], v[24:25], v[120:121], v[58:59] op_sel_hi:[1,0,1]
	v_pk_fma_f32 v[78:79], v[24:25], v[136:137], v[78:79] op_sel_hi:[1,0,1]
	v_pk_fma_f32 v[58:59], v[26:27], v[120:121], v[58:59] op_sel:[0,1,0]
	v_pk_fma_f32 v[78:79], v[26:27], v[136:137], v[78:79] op_sel:[0,1,0]
	s_waitcnt lgkmcnt(2)
	v_pk_fma_f32 v[58:59], v[30:31], v[122:123], v[58:59] op_sel_hi:[1,0,1]
	v_pk_fma_f32 v[78:79], v[30:31], v[138:139], v[78:79] op_sel_hi:[1,0,1]
	v_pk_fma_f32 v[58:59], v[20:21], v[122:123], v[58:59] op_sel:[0,1,0]
	v_pk_fma_f32 v[78:79], v[20:21], v[138:139], v[78:79] op_sel:[0,1,0]
	v_pk_fma_f32 v[58:59], v[16:17], v[124:125], v[58:59] op_sel_hi:[1,0,1]
	v_pk_fma_f32 v[78:79], v[16:17], v[140:141], v[78:79] op_sel_hi:[1,0,1]
	v_pk_fma_f32 v[58:59], v[18:19], v[124:125], v[58:59] op_sel:[0,1,0]
	v_pk_fma_f32 v[78:79], v[18:19], v[140:141], v[78:79] op_sel:[0,1,0]
	s_waitcnt lgkmcnt(1)
	v_pk_fma_f32 v[58:59], v[22:23], v[126:127], v[58:59] op_sel_hi:[1,0,1]
	v_pk_fma_f32 v[78:79], v[22:23], v[142:143], v[78:79] op_sel_hi:[1,0,1]
	v_pk_fma_f32 v[58:59], v[12:13], v[126:127], v[58:59] op_sel:[0,1,0]
	v_pk_fma_f32 v[78:79], v[12:13], v[142:143], v[78:79] op_sel:[0,1,0]
	v_pk_fma_f32 v[58:59], v[8:9], v[128:129], v[58:59] op_sel_hi:[1,0,1]
	v_pk_fma_f32 v[78:79], v[8:9], v[144:145], v[78:79] op_sel_hi:[1,0,1]
	v_pk_fma_f32 v[58:59], v[10:11], v[128:129], v[58:59] op_sel:[0,1,0]
	v_pk_fma_f32 v[78:79], v[10:11], v[144:145], v[78:79] op_sel:[0,1,0]
	s_waitcnt lgkmcnt(0)
	v_pk_fma_f32 v[58:59], v[14:15], v[130:131], v[58:59] op_sel_hi:[1,0,1]
	v_pk_fma_f32 v[78:79], v[14:15], v[146:147], v[78:79] op_sel_hi:[1,0,1]
	v_pk_fma_f32 v[58:59], v[4:5], v[130:131], v[58:59] op_sel:[0,1,0]
	v_pk_fma_f32 v[78:79], v[4:5], v[146:147], v[78:79] op_sel:[0,1,0]
	v_pk_fma_f32 v[58:59], v[0:1], v[132:133], v[58:59] op_sel_hi:[1,0,1]
	v_pk_fma_f32 v[78:79], v[0:1], v[148:149], v[78:79] op_sel_hi:[1,0,1]
	v_pk_fma_f32 v[58:59], v[2:3], v[132:133], v[58:59] op_sel:[0,1,0]
	v_pk_fma_f32 v[78:79], v[2:3], v[148:149], v[78:79] op_sel:[0,1,0]
	v_pk_add_f32 v[38:39], v[82:83], v[58:59]
	s_nop 0
	v_pk_mul_f32 v[80:81], v[6:7], v[38:39] op_sel:[0,1]
	s_nop 0
	v_pk_fma_f32 v[82:83], v[34:35], v[38:39], v[80:81] op_sel_hi:[1,0,1] neg_lo:[0,0,1]
	s_nop 0
	v_pk_add_f32 v[38:39], v[82:83], v[78:79]
	s_cmpk_eq_i32 s24, 0x800
	s_cbranch_scc0 .LBB0_436
	s_movk_i32 s21, 0x800
	s_mov_b64 s[24:25], 0
	s_and_b64 vcc, exec, s[22:23]
	s_cbranch_vccz .LBB0_435
	s_lshl_b32 s20, s20, 4
	s_or_b32 s20, s20, s31
	s_ashr_i32 s21, s20, 31
	s_lshl_b64 s[20:21], s[20:21], 16
	s_add_u32 s20, s28, s20
	s_addc_u32 s21, s29, s21
	s_lshl_b32 s22, s96, 3
	s_add_u32 s20, s20, s22
	s_addc_u32 s21, s21, 0
	s_add_i32 s30, s30, s92
	v_lshl_add_u64 v[0:1], v[32:33], 3, s[20:21]
	s_cmpk_gt_i32 s30, 0xfff
	global_store_dwordx2 v[0:1], v[38:39], off
	s_cbranch_scc0 .LBB0_434

; #define LAS __attribute__((address_space(3)))
; __device__ __forceinline__ unsigned cvt_pk_bf16(float lo, float hi) { f32x2 v = {lo, hi}; bf16x2_t b = __builtin_convertvector(v, bf16x2_t); return __builtin_bit_cast(unsigned, b); }
; template <bool PASSC>
; __device__ __forceinline__ void ssm_task(int task, const SsmW& W, const bf16_t* U, f32x2* SST, bf16_t* YS, LAS unsigned char* wl, int lane) {
;     ...
;         asm volatile("s_waitcnt lgkmcnt(0)" ::: "memory");
; #pragma unroll
;         for (int s = 0; s < 16; ++s) {
;             const f32x2 bu = *(const LAS f32x2*)(BU + s * 520 + 8 * lane);
;             const float nr = ar * xr - ai * xi + bu.x, ni = ar * xi + ai * xr + bu.y; xr = nr; xi = ni;
;             if (PASSC) *(LAS unsigned*)(xb + s * 272 + 4 * lane) = cvt_pk_bf16(xr, xi);
;         }
.LBB0_549:
	s_or_b64 exec, exec, s[6:7]
	s_waitcnt vmcnt(0) lgkmcnt(0)
	s_mov_b64 s[100:101], 0x9800000
	v_lshl_add_u64 v[96:97], v[58:59], 0, s[4:5]
	v_lshl_add_u64 v[96:97], v[96:97], 0, s[100:101]
	global_load_ushort v92, v[96:97], off
	global_load_ushort v93, v[96:97], off offset:512
	global_load_ushort v94, v[96:97], off offset:1024
	global_load_ushort v95, v[96:97], off offset:1536
	v_mfma_f32_16x16x32_bf16 v[84:87], v[48:51], v[4:7], 0
	v_add_u32_e32 v61, 0x400, v120
	s_mov_b32 s6, 0x9800000
	v_mfma_f32_16x16x32_bf16 v[88:91], v[48:51], v[0:3], 0
	s_nop 7
	ds_write2_b32 v119, v84, v88 offset1:16
	ds_write2_b32 v120, v85, v89 offset1:16
	ds_write2_b32 v120, v86, v90 offset0:130 offset1:146
	ds_write2_b32 v61, v87, v91 offset0:4 offset1:20
	v_mfma_f32_16x16x32_bf16 v[84:87], v[48:51], v[12:15], 0
	v_mfma_f32_16x16x32_bf16 v[88:91], v[48:51], v[8:11], 0
	s_nop 7
	ds_write2_b32 v119, v84, v88 offset0:32 offset1:48
	ds_write2_b32 v120, v85, v89 offset0:32 offset1:48
	ds_write2_b32 v120, v86, v90 offset0:162 offset1:178
	ds_write2_b32 v61, v87, v91 offset0:36 offset1:52
	v_mfma_f32_16x16x32_bf16 v[84:87], v[48:51], v[20:23], 0
	v_mfma_f32_16x16x32_bf16 v[88:91], v[48:51], v[16:19], 0
	s_nop 7
	ds_write2_b32 v119, v84, v88 offset0:64 offset1:80
	ds_write2_b32 v120, v85, v89 offset0:64 offset1:80
	ds_write2_b32 v120, v86, v90 offset0:194 offset1:210
	ds_write2_b32 v61, v87, v91 offset0:68 offset1:84
	v_mfma_f32_16x16x32_bf16 v[84:87], v[48:51], v[28:31], 0
	v_mfma_f32_16x16x32_bf16 v[48:51], v[48:51], v[24:27], 0
	s_nop 7
	ds_write2_b32 v119, v84, v48 offset0:96 offset1:112
	ds_write2_b32 v120, v85, v49 offset0:96 offset1:112
	ds_write2_b32 v120, v86, v50 offset0:226 offset1:242
	ds_write2_b32 v61, v87, v51 offset0:100 offset1:116
	s_waitcnt lgkmcnt(0)
	ds_read_b64 v[48:49], v121
	ds_read_b64 v[50:51], v121 offset:520
	v_pk_mul_f32 v[62:63], v[54:55], v[82:83] op_sel_hi:[1,0]
	s_nop 0
	v_pk_fma_f32 v[84:85], v[76:77], v[80:81], v[62:63] op_sel_hi:[1,0,1] neg_lo:[0,0,1]
	s_waitcnt lgkmcnt(1)
	v_pk_add_f32 v[80:81], v[84:85], v[48:49]
	ds_read_b64 v[86:87], v121 offset:1040
	v_pk_mul_f32 v[62:63], v[78:79], v[80:81]
	v_cvt_pk_bf16_f32 v89, v80, v81
	v_pk_fma_f32 v[84:85], v[52:53], v[80:81], v[62:63] op_sel:[0,0,1] op_sel_hi:[1,1,0] neg_lo:[0,0,1]
	ds_write_b32 v122, v89 offset:8320
	s_waitcnt lgkmcnt(2)
	v_pk_add_f32 v[80:81], v[50:51], v[84:85]
	ds_read_b64 v[48:49], v121 offset:1560
	v_pk_mul_f32 v[62:63], v[78:79], v[80:81]
	v_cvt_pk_bf16_f32 v88, v80, v81
	v_pk_fma_f32 v[84:85], v[52:53], v[80:81], v[62:63] op_sel:[0,0,1] op_sel_hi:[1,1,0] neg_lo:[0,0,1]
	ds_write_b32 v122, v88 offset:8592
	s_waitcnt lgkmcnt(3)
	v_pk_add_f32 v[80:81], v[86:87], v[84:85]
	ds_read_b64 v[50:51], v121 offset:2080
	v_pk_mul_f32 v[62:63], v[78:79], v[80:81]
	v_cvt_pk_bf16_f32 v89, v80, v81
	v_pk_fma_f32 v[84:85], v[52:53], v[80:81], v[62:63] op_sel:[0,0,1] op_sel_hi:[1,1,0] neg_lo:[0,0,1]
	ds_write_b32 v122, v89 offset:8864
	s_waitcnt lgkmcnt(3)
	v_pk_add_f32 v[80:81], v[48:49], v[84:85]
	ds_read_b64 v[86:87], v121 offset:2600
	v_pk_mul_f32 v[62:63], v[78:79], v[80:81]
	v_cvt_pk_bf16_f32 v88, v80, v81
	v_pk_fma_f32 v[84:85], v[52:53], v[80:81], v[62:63] op_sel:[0,0,1] op_sel_hi:[1,1,0] neg_lo:[0,0,1]
	ds_write_b32 v122, v88 offset:9136
	s_waitcnt lgkmcnt(3)
	v_pk_add_f32 v[80:81], v[50:51], v[84:85]
	ds_read_b64 v[48:49], v121 offset:3120
	v_pk_mul_f32 v[62:63], v[78:79], v[80:81]
	v_cvt_pk_bf16_f32 v89, v80, v81
	v_pk_fma_f32 v[84:85], v[52:53], v[80:81], v[62:63] op_sel:[0,0,1] op_sel_hi:[1,1,0] neg_lo:[0,0,1]
	ds_write_b32 v122, v89 offset:9408
	s_waitcnt lgkmcnt(3)
	v_pk_add_f32 v[80:81], v[86:87], v[84:85]
	ds_read_b64 v[50:51], v121 offset:3640
	v_pk_mul_f32 v[62:63], v[78:79], v[80:81]
	v_cvt_pk_bf16_f32 v88, v80, v81
	v_pk_fma_f32 v[84:85], v[52:53], v[80:81], v[62:63] op_sel:[0,0,1] op_sel_hi:[1,1,0] neg_lo:[0,0,1]
	ds_write_b32 v122, v88 offset:9680
	s_waitcnt lgkmcnt(3)
	v_pk_add_f32 v[80:81], v[48:49], v[84:85]
	ds_read_b64 v[86:87], v121 offset:4160
	v_pk_mul_f32 v[62:63], v[78:79], v[80:81]
	v_cvt_pk_bf16_f32 v89, v80, v81
	v_pk_fma_f32 v[84:85], v[52:53], v[80:81], v[62:63] op_sel:[0,0,1] op_sel_hi:[1,1,0] neg_lo:[0,0,1]
	ds_write_b32 v122, v89 offset:9952
	s_waitcnt lgkmcnt(3)
; #define LAS __attribute__((address_space(3)))
; __device__ __forceinline__ unsigned cvt_pk_bf16(float lo, float hi) { f32x2 v = {lo, hi}; bf16x2_t b = __builtin_convertvector(v, bf16x2_t); return __builtin_bit_cast(unsigned, b); }
; __device__ __forceinline__ bf16_t f2bf(float f) { unsigned u = __builtin_bit_cast(unsigned, f); return (bf16_t)((u + 0x7fffu + ((u >> 16) & 1u)) >> 16); }
; #define MFMA16(a, b, c) __builtin_amdgcn_mfma_f32_16x16x32_bf16((a), (b), (c), 0, 0, 0)
; template <bool PASSC>
; __device__ __forceinline__ void ssm_task(int task, const SsmW& W, const bf16_t* U, f32x2* SST, bf16_t* YS, LAS unsigned char* wl, int lane) {
;     ...
;         asm volatile("s_waitcnt lgkmcnt(0)" ::: "memory");
; #pragma unroll
;         for (int s = 0; s < 16; ++s) {
;             const f32x2 bu = *(const LAS f32x2*)(BU + s * 520 + 8 * lane);
;             const float nr = ar * xr - ai * xi + bu.x, ni = ar * xi + ai * xr + bu.y; xr = nr; xi = ni;
;             if (PASSC) *(LAS unsigned*)(xb + s * 272 + 4 * lane) = cvt_pk_bf16(xr, xi);
;         }
;         if (PASSC) {
;             asm volatile("s_waitcnt lgkmcnt(0)" ::: "memory");
;             f32x4 y = (f32x4){0.f, 0.f, 0.f, 0.f};
; #pragma unroll
;             for (int ks = 0; ks < 4; ++ks) { const bf16x8 a0 = *(const LAS bf16x8*)(xb + hh * 272 + 64 * ks + 16 * kq); y = MFMA16(a0, cf[ks], y); }
; #pragma unroll
;             for (int i = 0; i < 4; ++i) {
;                 const size_t e = (size_t)(4 * kq + i) * 256 + hh;
;                 YS[(tok0 + blk * 16) * 256 + g * 16 + e] = f2bf(y[i] + dk * bf2f(ub[e]));
;             }
;         }
	v_pk_add_f32 v[80:81], v[50:51], v[84:85]
	ds_read_b64 v[48:49], v121 offset:4680
	v_pk_mul_f32 v[62:63], v[78:79], v[80:81]
	v_cvt_pk_bf16_f32 v88, v80, v81
	v_pk_fma_f32 v[84:85], v[52:53], v[80:81], v[62:63] op_sel:[0,0,1] op_sel_hi:[1,1,0] neg_lo:[0,0,1]
	ds_write_b32 v122, v88 offset:10224
	s_waitcnt lgkmcnt(3)
	v_pk_add_f32 v[80:81], v[86:87], v[84:85]
	ds_read_b64 v[50:51], v121 offset:5200
	v_pk_mul_f32 v[62:63], v[78:79], v[80:81]
	v_cvt_pk_bf16_f32 v89, v80, v81
	v_pk_fma_f32 v[84:85], v[52:53], v[80:81], v[62:63] op_sel:[0,0,1] op_sel_hi:[1,1,0] neg_lo:[0,0,1]
	ds_write_b32 v122, v89 offset:10496
	s_waitcnt lgkmcnt(3)
	v_pk_add_f32 v[80:81], v[48:49], v[84:85]
	ds_read_b64 v[86:87], v121 offset:5720
	v_pk_mul_f32 v[62:63], v[78:79], v[80:81]
	v_cvt_pk_bf16_f32 v88, v80, v81
	v_pk_fma_f32 v[84:85], v[52:53], v[80:81], v[62:63] op_sel:[0,0,1] op_sel_hi:[1,1,0] neg_lo:[0,0,1]
	ds_write_b32 v122, v88 offset:10768
	s_waitcnt lgkmcnt(3)
	v_pk_add_f32 v[80:81], v[50:51], v[84:85]
	ds_read_b64 v[48:49], v121 offset:6240
	v_pk_mul_f32 v[62:63], v[78:79], v[80:81]
	v_cvt_pk_bf16_f32 v89, v80, v81
	v_pk_fma_f32 v[84:85], v[52:53], v[80:81], v[62:63] op_sel:[0,0,1] op_sel_hi:[1,1,0] neg_lo:[0,0,1]
	ds_write_b32 v122, v89 offset:11040
	s_waitcnt lgkmcnt(3)
	v_pk_add_f32 v[80:81], v[86:87], v[84:85]
	ds_read_b64 v[50:51], v121 offset:6760
	v_pk_mul_f32 v[62:63], v[78:79], v[80:81]
	v_cvt_pk_bf16_f32 v88, v80, v81
	v_pk_fma_f32 v[84:85], v[52:53], v[80:81], v[62:63] op_sel:[0,0,1] op_sel_hi:[1,1,0] neg_lo:[0,0,1]
	ds_write_b32 v122, v88 offset:11312
	s_waitcnt lgkmcnt(3)
	v_pk_add_f32 v[80:81], v[48:49], v[84:85]
	ds_read_b64 v[86:87], v121 offset:7280
	v_pk_mul_f32 v[62:63], v[78:79], v[80:81]
	v_cvt_pk_bf16_f32 v89, v80, v81
	v_pk_fma_f32 v[84:85], v[52:53], v[80:81], v[62:63] op_sel:[0,0,1] op_sel_hi:[1,1,0] neg_lo:[0,0,1]
	ds_write_b32 v122, v89 offset:11584
	s_waitcnt lgkmcnt(3)
	v_pk_add_f32 v[80:81], v[50:51], v[84:85]
	ds_read_b64 v[48:49], v121 offset:7800
	v_pk_mul_f32 v[62:63], v[78:79], v[80:81]
	v_cvt_pk_bf16_f32 v88, v80, v81
	v_pk_fma_f32 v[84:85], v[52:53], v[80:81], v[62:63] op_sel:[0,0,1] op_sel_hi:[1,1,0] neg_lo:[0,0,1]
	ds_write_b32 v122, v88 offset:11856
	s_waitcnt lgkmcnt(3)
	v_pk_add_f32 v[80:81], v[86:87], v[84:85]
	s_nop 0
	v_pk_mul_f32 v[62:63], v[78:79], v[80:81]
	v_cvt_pk_bf16_f32 v89, v80, v81
	v_pk_fma_f32 v[84:85], v[52:53], v[80:81], v[62:63] op_sel:[0,0,1] op_sel_hi:[1,1,0] neg_lo:[0,0,1]
	ds_write_b32 v122, v89 offset:12128
	s_waitcnt lgkmcnt(2)
	v_pk_add_f32 v[80:81], v[48:49], v[84:85]
	s_nop 0
	v_lshl_add_u64 v[62:63], v[58:59], 0, s[4:5]
	s_add_u32 s4, s4, 0x2000
	v_cvt_pk_bf16_f32 v48, v80, v81
	ds_write_b32 v122, v48 offset:12400
	s_waitcnt lgkmcnt(0)
	ds_read_b128 v[48:51], v123 offset:8320
	ds_read_b128 v[84:87], v123 offset:8384
	ds_read_b128 v[98:101], v123 offset:8448
	ds_read_b128 v[102:105], v123 offset:8512
	s_waitcnt lgkmcnt(3)
	v_mfma_f32_16x16x32_bf16 v[48:51], v[48:51], v[32:35], 0
	s_addc_u32 s5, s5, 0
	s_cmpk_lg_u32 s4, 0x8000
	v_mov_b32_e32 v82, v81
	s_waitcnt lgkmcnt(2)
	v_mfma_f32_16x16x32_bf16 v[48:51], v[84:87], v[36:39], v[48:51]
	s_waitcnt lgkmcnt(1)
	v_mfma_f32_16x16x32_bf16 v[48:51], v[98:101], v[40:43], v[48:51]
	s_waitcnt lgkmcnt(0)
	v_mfma_f32_16x16x32_bf16 v[48:51], v[102:105], v[44:47], v[48:51]
	v_add_co_u32_e32 v84, vcc, s6, v62
	s_mov_b32 s6, 0xa800000
	s_nop 0
	v_addc_co_u32_e32 v85, vcc, 0, v63, vcc
	v_add_co_u32_e32 v62, vcc, s6, v62
	s_waitcnt vmcnt(0)
	s_nop 1
	v_lshlrev_b32_e32 v61, 16, v92
	v_fma_f32 v48, v60, v61, v48
	v_bfe_u32 v61, v48, 16, 1
	v_add3_u32 v48, v48, v61, s52
	v_addc_co_u32_e32 v63, vcc, 0, v63, vcc
	global_store_short_d16_hi v[62:63], v48, off
	v_lshlrev_b32_e32 v48, 16, v93
	v_fma_f32 v48, v60, v48, v49
	v_bfe_u32 v49, v48, 16, 1
	v_add3_u32 v48, v48, v49, s52
	global_store_short_d16_hi v[62:63], v48, off offset:512
	v_lshlrev_b32_e32 v48, 16, v94
	v_fma_f32 v48, v60, v48, v50
	v_bfe_u32 v49, v48, 16, 1
	v_add3_u32 v48, v48, v49, s52
	global_store_short_d16_hi v[62:63], v48, off offset:1024
	v_lshlrev_b32_e32 v48, 16, v95
	v_fmac_f32_e32 v51, v60, v48
	v_bfe_u32 v48, v51, 16, 1
	v_add3_u32 v48, v51, v48, s52
	global_store_short_d16_hi v[62:63], v48, off offset:1536
	s_waitcnt lgkmcnt(0)
	s_cbranch_scc0 .LBB0_497
